# sample-path units deferred until after the mid-P2 grid barrier (they only feed P3), so the barrier pole is the chain<0> pass; on top of batched fold etc
# speedup vs baseline: 1.0143x; 1.0013x over previous
; #define TIDX(wv) ((wv) * 64 + lane_id_asm())
; #define LAS __attribute__((address_space(3)))
; __global__ void __launch_bounds__(512, 2) fwd_kernel(Args args) {
;     extern __shared__ __attribute__((aligned(16))) unsigned char lds[];
;     LAS unsigned char* ldsl = (LAS unsigned char*)lds;
;     volatile LAS unsigned* MISC = (volatile LAS unsigned*)(ldsl + MISC_OFF);
;     const int wave = __builtin_amdgcn_readfirstlane((int)threadIdx.x >> 6);
;     ...
;     const int G = gridDim.x, bx = blockIdx.x; const int vcu = (G % 8 == 0) ? (bx % 8) * (G / 8) + bx / 8 : bx;
;     const int gw = vcu * 8 + wave, NGW = G * 8;
;     if (TIDX(wave) < 32) MISC[TIDX(wave)] = 0u;
_Z10fwd_kernel4Args:
	v_mov_b32_e32 v247, 0
	s_load_dword s88, s[0:1], 0x100
	s_add_u32 s4, s0, 0x100
	v_and_b32_e32 v188, 0x3ff, v0
	s_addc_u32 s5, s1, 0
	v_readfirstlane_b32 s52, v188
	s_waitcnt lgkmcnt(0)
	s_and_b32 s3, s88, 7
	v_writelane_b32 v246, s4, 0
	s_cmp_lg_u32 s3, 0
	s_mov_b32 s3, s2
	v_writelane_b32 v246, s5, 1
	s_cbranch_scc1 .LBB0_2
	s_ashr_i32 s4, s2, 31
	s_lshr_b32 s4, s4, 29
	s_add_i32 s4, s2, s4
	s_and_b32 s5, s4, -8
	s_ashr_i32 s3, s88, 3
	s_sub_i32 s5, s2, s5
	s_mul_i32 s3, s3, s5
	s_ashr_i32 s4, s4, 3
	s_add_i32 s3, s3, s4

; #define GSYNC() xcd_barrier(xbar, TIDX(wave) == 0)
; #define cK karg(2)
; #define cV karg(3)
; #define cF karg(4)
; #define S0 karg(5)
; __global__ void __launch_bounds__(512, 2) fwd_kernel(Args args) {
;     ...
;         if (mixm & 2) { for (int c = bx; c < 64; c += G) attn_body::cb_scan(c >> 3, c & 7, out + O_FP, (float*)(ws + WS_CBG), (char*)lds, wave); }
;         if (mixm & 1) {
;             for (int it = bx; it < 224; it += G) gla::chain<0>((it & 31) >> 2, it & 3, it >> 5, (float*)(ws + WS_SLOC), (float*)(ws + WS_DTOT), QB, KB, VB, OBG, RB, A1, w_a2, b_a2, g_gla, out + O_SP, (char*)lds, wave);
;             if (bx >= 224 || G < 256) {
;                 const int nb = G < 256 ? G : G - 224, b0 = G < 256 ? bx : bx - 224;
;                 if (mixm & 4) { for (int u = b0; u < 64; u += nb) sattn::unit(u >> 3, u & 7, QA, OA, cK, cV, cF, out, (char*)lds, wave); }
;                 if (mixm & 8) { for (int u = b0; u < 32; u += nb) gla::sample_unit(u >> 2, u & 3, QB, KB, VB, OBG, RB, A1, w_a2, b_a2, g_gla, S0, out + O_SS, (char*)lds, wave); } }
;             GSYNC();
.Lsamp_ret:
	s_mov_b32 s12, 2
	s_nop 0
	v_writelane_b32 v247, s12, 5
	s_branch .Lpost_gsync
.LBB0_494:
	s_cmpk_gt_i32 s2, 0xdf
	s_cselect_b64 s[6:7], -1, 0
	s_cmpk_lt_i32 s88, 0x100
	s_cselect_b64 s[4:5], -1, 0
	v_readlane_b32 s74, v246, 27
	s_or_b64 s[6:7], s[6:7], s[4:5]
	s_lshl_b32 s8, s74, 2
	s_add_i32 s30, s8, 0x100
	s_and_b64 vcc, exec, s[6:7]
	v_readlane_b32 s75, v246, 28
	v_writelane_b32 v245, s30, 59
	v_readlane_b32 s12, v247, 5
	s_nop 3
	s_cmp_eq_u32 s12, 0
	s_cbranch_scc1 .LBB0_598
	s_cbranch_vccz .LBB0_598
	s_add_i32 s8, s88, 0xffffff20
	s_and_b64 s[6:7], s[4:5], exec
	s_cselect_b32 s78, s88, s8
	s_add_i32 s6, s2, 0xffffff20
	s_and_b64 s[4:5], s[4:5], exec
	s_cselect_b32 s8, s2, s6
	s_cmp_gt_i32 s8, 63
	s_cbranch_scc1 .LBB0_555
	v_readlane_b32 s4, v246, 14
	s_cmpk_gt_u32 s4, 0x103f
	v_readlane_b32 s4, v246, 4
	s_mov_b32 s6, s4
	s_mulk_i32 s4, 0x107c
	v_mbcnt_lo_u32_b32 v1, -1, 0
	s_cselect_b64 s[34:35], -1, 0
	s_add_i32 s9, s10, s4
	s_lshl_b32 s4, s6, 7
	v_mbcnt_hi_u32_b32 v33, -1, v1
	s_add_i32 s29, s6, -8
	s_add_i32 s31, s4, 0x100
	s_mov_b32 s93, 0
	s_movk_i32 s21, 0x810
	v_mov_b32_e32 v31, 0
	v_and_b32_e32 v35, 64, v33
	v_add_u32_e32 v41, -1, v33
	v_add_u32_e32 v44, -2, v33
	v_add_u32_e32 v45, -4, v33
	v_add_u32_e32 v46, -8, v33
	s_mov_b32 s36, 0xbfb8aa3b
	s_mov_b32 s22, 0xf149f2ca
	s_mov_b32 s23, 0xefa18f08
	s_mov_b32 s24, 0xc2fc0000
	v_add_u32_e32 v47, -16, v33
	v_mov_b32_e32 v48, 0x100
	v_mov_b32_e32 v49, 0xf149f2ca
	v_mov_b32_e32 v50, 0x42800000
	v_not_b32_e32 v51, 63
	s_mov_b32 s25, s8
	v_readlane_b32 s5, v246, 5
	s_branch .LBB0_498

; __device__ __forceinline__ void xcd_barrier(const XcdBarrier& b, bool t0) {
;     asm volatile("s_waitcnt vmcnt(0)" ::: "memory");
;     __syncthreads();
;     if (t0) {
;         unsigned* bar = b.bar;
;         __builtin_amdgcn_s_waitcnt(0);
;         unsigned nloc = b.st[0], nx = b.st[1];
;         if (nloc == 0u) { xcd_barrier_complete(bar, b.x, nloc, nx); b.st[0] = nloc; b.st[1] = nx; }
.LBB0_598:
	v_readlane_b32 s12, v247, 5
	s_nop 3
	s_cmp_eq_u32 s12, 1
	s_cbranch_scc1 .Lsamp_ret
	v_mbcnt_lo_u32_b32 v1, -1, 0
	v_mbcnt_hi_u32_b32 v1, -1, v1
	s_waitcnt vmcnt(0)
	s_waitcnt vmcnt(0)
	v_sub_u32_e32 v1, 0, v1
	v_cmp_eq_u32_e32 vcc, s74, v1
	s_barrier
	s_and_saveexec_b64 s[4:5], vcc
	v_readlane_b32 s76, v246, 25
	s_cbranch_execz .LBB0_650
	s_mov_b32 s6, 0x20160
	s_addk_i32 s6, 0x100
	v_mov_b32_e32 v1, s6
	s_mov_b32 s6, 0x20164
	s_waitcnt vmcnt(0) expcnt(0) lgkmcnt(0)
	ds_read_b32 v3, v1
	s_addk_i32 s6, 0x100
	v_mov_b32_e32 v1, s6
	ds_read_b32 v2, v1
	s_waitcnt lgkmcnt(1)
	v_cmp_ne_u32_e32 vcc, 0, v3
	s_cbranch_vccnz .LBB0_614
	v_readlane_b32 s8, v246, 0
	v_readlane_b32 s9, v246, 1
	s_load_dwordx2 s[6:7], s[8:9], 0x4
	s_mov_b32 s13, 1
	v_mov_b32_e32 v17, 0
	s_waitcnt lgkmcnt(0)
	s_mul_i32 s12, s6, s88
	s_mul_i32 s12, s12, s7
	s_branch .LBB0_602

; #define GSYNC() xcd_barrier(xbar, TIDX(wave) == 0)
; __device__ __forceinline__ void xcd_barrier(const XcdBarrier& b, bool t0) {
;     ...
;     __syncthreads();
; }
; __global__ void __launch_bounds__(512, 2) fwd_kernel(Args args) {
;     ...
;             GSYNC();
;             for (int it = bx; it < 256; it += G) gla::chain<1>((it & 31) >> 2, it & 3, it >> 5, (float*)(ws + WS_SLOC), (float*)(ws + WS_DTOT), QB, KB, VB, OBG, RB, A1, w_a2, b_a2, g_gla, out + O_SP, (char*)lds, wave); }
.LBB0_650:
	s_or_b64 exec, exec, s[4:5]
	v_readlane_b32 s4, v245, 41
	v_readlane_b32 s5, v245, 42
	s_andn2_b64 vcc, exec, s[4:5]
	s_waitcnt lgkmcnt(0)
	s_barrier
	v_readlane_b32 s12, v247, 5
	s_nop 3
	s_cmp_lg_u32 s12, 0
	s_cbranch_scc1 .Lpost_gsync
	s_cmpk_lt_i32 s2, 0xe0
	s_cbranch_scc1 .Lpost_gsync
	s_mov_b32 s12, 1
	s_nop 0
	v_writelane_b32 v247, s12, 5
	s_branch .LBB0_494
.Lpost_gsync:
	v_readlane_b32 s4, v245, 41
	v_readlane_b32 s5, v245, 42
	s_nop 3
	s_andn2_b64 vcc, exec, s[4:5]
	s_cbranch_vccnz .LBB0_685
	v_readlane_b32 s4, v246, 53
	v_writelane_b32 v245, s61, 60
	s_mov_b32 s90, s11
	s_and_b32 s10, s11, 0x1ffffff0
	s_and_b32 s11, s4, 32
	s_add_i32 s4, s30, 0x19600
	v_readlane_b32 s12, v246, 4
	v_writelane_b32 v245, s4, 49
	v_readlane_b32 s13, v246, 5
	s_lshl_b32 s4, s12, 8
	s_mov_b32 s9, 0
	v_readlane_b32 s5, v246, 54
	s_addk_i32 s4, 0x100
	s_mov_b32 s13, s9
	s_add_i32 s87, s4, 0x19e00
	s_lshl_b64 s[4:5], s[12:13], 7
	s_add_u32 s4, s4, 0x3dc00000
	v_writelane_b32 v245, s4, 61
	s_addc_u32 s4, s5, 0
	v_writelane_b32 v245, s4, 63
	s_lshl_b64 s[4:5], s[12:13], 12
	v_writelane_b32 v245, s4, 47
	s_mov_b32 s6, 0x19600
	v_mbcnt_lo_u32_b32 v1, -1, 0
	v_writelane_b32 v245, s5, 48
	s_mov_b32 s4, s12
	v_writelane_b32 v246, s4, 4
	s_movk_i32 s91, 0x100
	s_mul_i32 s79, s12, 0x880
	v_writelane_b32 v246, s5, 5
	s_lshl_b64 s[4:5], s[12:13], 9
	v_writelane_b32 v244, s4, 1
	s_lshl_b64 s[72:73], s[12:13], 13
	v_mov_b32_e32 v3, 0
	v_writelane_b32 v244, s5, 2
	s_mov_b32 s4, 0x1a600
	s_addk_i32 s4, 0x100
	v_writelane_b32 v244, s4, 3
	s_mov_b32 s4, 0x18400
	s_addk_i32 s4, 0x100
	v_writelane_b32 v245, s4, 45
	s_mov_b32 s4, 0x19400
	s_addk_i32 s4, 0x100
	s_mov_b32 s81, 0x16000
	v_writelane_b32 v246, s4, 14
	s_mov_b32 s18, 0xbfb8aa3b
	s_mov_b32 s21, 0x800000
	s_mov_b32 s20, 0x3f317217
	s_mov_b32 s19, 0x7f800000
	s_mov_b32 s78, 0x3d800000
	s_mov_b32 s80, 0x3db504f3
	v_mbcnt_hi_u32_b32 v1, -1, v1
	v_mov_b32_e32 v144, 0x3727c5ac
	s_mov_b32 s22, 0xf800000
	v_mov_b32_e32 v145, 0x260
	v_mov_b32_e32 v146, 0x100
	s_add_i32 s4, s6, 0x100
	v_mov_b32_e32 v147, 0x41b17218
	s_mov_b32 s23, s2
	s_mov_b32 s24, s2
	v_writelane_b32 v245, s4, 57
	s_branch .LBB0_653

; __global__ void __launch_bounds__(512, 2) fwd_kernel(Args args) {
;     extern __shared__ __attribute__((aligned(16))) unsigned char lds[];
	.amdhsa_kernel _Z10fwd_kernel4Args
		.amdhsa_group_segment_fixed_size 256
		.amdhsa_private_segment_fixed_size 0
		.amdhsa_kernarg_size 512
		.amdhsa_user_sgpr_count 2
		.amdhsa_user_sgpr_dispatch_ptr 0
		.amdhsa_user_sgpr_queue_ptr 0
		.amdhsa_user_sgpr_kernarg_segment_ptr 1
		.amdhsa_user_sgpr_dispatch_id 0
		.amdhsa_user_sgpr_kernarg_preload_length 0
		.amdhsa_user_sgpr_kernarg_preload_offset 0
		.amdhsa_user_sgpr_private_segment_size 0
		.amdhsa_uses_dynamic_stack 0
		.amdhsa_enable_private_segment 0
		.amdhsa_system_sgpr_workgroup_id_x 1
		.amdhsa_system_sgpr_workgroup_id_y 0
		.amdhsa_system_sgpr_workgroup_id_z 0
		.amdhsa_system_sgpr_workgroup_info 0
		.amdhsa_system_vgpr_workitem_id 2
		.amdhsa_next_free_vgpr 248
		.amdhsa_next_free_sgpr 98
		.amdhsa_accum_offset 248
		.amdhsa_reserve_vcc 1
		.amdhsa_float_round_mode_32 0
		.amdhsa_float_round_mode_16_64 0
		.amdhsa_float_denorm_mode_32 3
		.amdhsa_float_denorm_mode_16_64 3
		.amdhsa_dx10_clamp 1
		.amdhsa_ieee_mode 1
		.amdhsa_fp16_overflow 0
		.amdhsa_tg_split 0
		.amdhsa_exception_fp_ieee_invalid_op 0
		.amdhsa_exception_fp_denorm_src 0
		.amdhsa_exception_fp_ieee_div_zero 0
		.amdhsa_exception_fp_ieee_overflow 0
		.amdhsa_exception_fp_ieee_underflow 0
		.amdhsa_exception_fp_ieee_inexact 0
		.amdhsa_exception_int_div_zero 0
	.end_amdhsa_kernel

; #define KAS __attribute__((address_space(4)))
; __device__ __forceinline__ const float* karg(int i) { const KAS char* ka = (const KAS char*)__builtin_amdgcn_kernarg_segment_ptr(); const unsigned long long v = *(const unsigned long long volatile KAS*)(ka + 8 * i); return (const float*)(const __attribute__((address_space(1))) float*)v; }
; __device__ __forceinline__ int kargi(int byteoff) { const KAS char* ka = (const KAS char*)__builtin_amdgcn_kernarg_segment_ptr(); return *(const int volatile KAS*)(ka + byteoff); }
; __global__ void __launch_bounds__(512, 2) fwd_kernel(Args args) {
;     extern __shared__ __attribute__((aligned(16))) unsigned char lds[];
amdhsa.kernels:
  - .agpr_count:     0
    .args:
      - .offset:         0
        .size:           256
        .value_kind:     by_value
      - .offset:         256
        .size:           4
        .value_kind:     hidden_block_count_x
      - .offset:         260
        .size:           4
        .value_kind:     hidden_block_count_y
      - .offset:         264
        .size:           4
        .value_kind:     hidden_block_count_z
      - .offset:         268
        .size:           2
        .value_kind:     hidden_group_size_x
      - .offset:         270
        .size:           2
        .value_kind:     hidden_group_size_y
      - .offset:         272
        .size:           2
        .value_kind:     hidden_group_size_z
      - .offset:         274
        .size:           2
        .value_kind:     hidden_remainder_x
      - .offset:         276
        .size:           2
        .value_kind:     hidden_remainder_y
      - .offset:         278
        .size:           2
        .value_kind:     hidden_remainder_z
      - .offset:         296
        .size:           8
        .value_kind:     hidden_global_offset_x
      - .offset:         304
        .size:           8
        .value_kind:     hidden_global_offset_y
      - .offset:         312
        .size:           8
        .value_kind:     hidden_global_offset_z
      - .offset:         320
        .size:           2
        .value_kind:     hidden_grid_dims
      - .offset:         344
        .size:           8
        .value_kind:     hidden_multigrid_sync_arg
      - .offset:         376
        .size:           4
        .value_kind:     hidden_dynamic_lds_size
    .group_segment_fixed_size: 256
    .kernarg_segment_align: 8
    .kernarg_segment_size: 512
    .language:       OpenCL C
    .language_version:
      - 2
      - 0
    .max_flat_workgroup_size: 512
    .name:           _Z10fwd_kernel4Args
    .private_segment_fixed_size: 0
    .sgpr_count:     104
    .sgpr_spill_count: 197
    .symbol:         _Z10fwd_kernel4Args.kd
    .uniform_work_group_size: 1
    .uses_dynamic_stack: false
    .vgpr_count:     248
    .vgpr_spill_count: 0
    .wavefront_size: 64
